# hot loop heads (GEMM K loops, scan chunk loop, attention tile loop) aligned to 64 bytes
# speedup vs baseline: 1.0048x; 1.0017x over previous
; template <class Epi, class Sched, bool ALIGN_EPI = false, bool SP2 = false>
; __device__ __forceinline__ void gemm_phase(PG8_LAS unsigned char* lds, const Gemm g, const Sched& S, const Epi& E, const int tid_in) {
;     ...
;         const bool has_next = S.next(ui + 1, nxt);
;         const char* nA = has_next ? (const char*)g.asel(nxt.pn) + (size_t)nxt.pm * tstep : cA; const char* nB = has_next ? (const char*)g.Bt + (size_t)nxt.pn * tstep : cB;
;     ...
; #pragma unroll
;         for (int a = 0; a < 2; ++a)
; #pragma unroll
;             for (int b = 0; b < 2; ++b)
; #pragma unroll
;                 for (int m = 0; m < 4; ++m)
; #pragma unroll
;                     for (int n = 0; n < 2; ++n) acc[a][b][m][n] = (f32x4){0.f, 0.f, 0.f, 0.f};
;         cur = nxt; cA = nA; cB = nB; ++ui;
.LBB0_126:
	s_ashr_i32 s25, s24, 31
	s_lshl_b64 s[26:27], s[24:25], 19
	s_add_u32 s26, s39, s26
	s_addc_u32 s27, s40, s27
	s_and_b64 s[28:29], s[2:3], exec
	s_cselect_b32 s5, s27, s1
	s_cselect_b32 s25, s26, s0
	s_ashr_i32 s23, s22, 31
	s_lshl_b64 s[28:29], s[22:23], 19
	s_add_u32 s28, s8, s28
	s_addc_u32 s29, s9, s29
	s_and_b64 s[36:37], s[2:3], exec
	s_cselect_b32 s23, s29, s35
	s_cselect_b32 s56, s28, s34
	s_add_u32 s0, s0, 0x40080
	s_addc_u32 s1, s1, 0
	s_add_u32 s57, s34, 0x100
	v_mov_b32_e32 v0, 0
	s_addc_u32 s58, s35, 0
	s_mov_b32 s59, -2
	v_mov_b32_e32 v1, v0
	v_mov_b32_e32 v2, v0
	v_mov_b32_e32 v3, v0
	v_mov_b32_e32 v4, v0
	v_mov_b32_e32 v5, v0
	v_mov_b32_e32 v6, v0
	v_mov_b32_e32 v7, v0
	v_mov_b32_e32 v16, v0
	v_mov_b32_e32 v17, v0
	v_mov_b32_e32 v18, v0
	v_mov_b32_e32 v19, v0
	v_mov_b32_e32 v20, v0
	v_mov_b32_e32 v21, v0
	v_mov_b32_e32 v22, v0
	v_mov_b32_e32 v23, v0
	v_mov_b32_e32 v32, v0
	v_mov_b32_e32 v33, v0
	v_mov_b32_e32 v34, v0
	v_mov_b32_e32 v35, v0
	v_mov_b32_e32 v36, v0
	v_mov_b32_e32 v37, v0
	v_mov_b32_e32 v38, v0
	v_mov_b32_e32 v39, v0
	v_mov_b32_e32 v48, v0
	v_mov_b32_e32 v49, v0
	v_mov_b32_e32 v50, v0
	v_mov_b32_e32 v51, v0
	v_mov_b32_e32 v52, v0
	v_mov_b32_e32 v53, v0
	v_mov_b32_e32 v54, v0
	v_mov_b32_e32 v55, v0
	v_mov_b32_e32 v8, v0
	v_mov_b32_e32 v9, v0
	v_mov_b32_e32 v10, v0
	v_mov_b32_e32 v11, v0
	v_mov_b32_e32 v12, v0
	v_mov_b32_e32 v13, v0
	v_mov_b32_e32 v14, v0
	v_mov_b32_e32 v15, v0
	v_mov_b32_e32 v24, v0
	v_mov_b32_e32 v25, v0
	v_mov_b32_e32 v26, v0
	v_mov_b32_e32 v27, v0
	v_mov_b32_e32 v28, v0
	v_mov_b32_e32 v29, v0
	v_mov_b32_e32 v30, v0
	v_mov_b32_e32 v31, v0
	v_mov_b32_e32 v40, v0
	v_mov_b32_e32 v41, v0
	v_mov_b32_e32 v42, v0
	v_mov_b32_e32 v43, v0
	v_mov_b32_e32 v44, v0
	v_mov_b32_e32 v45, v0
	v_mov_b32_e32 v46, v0
	v_mov_b32_e32 v47, v0
	v_mov_b32_e32 v56, v0
	v_mov_b32_e32 v57, v0
	v_mov_b32_e32 v58, v0
	v_mov_b32_e32 v59, v0
	v_mov_b32_e32 v60, v0
	v_mov_b32_e32 v61, v0
	v_mov_b32_e32 v62, v0
	v_mov_b32_e32 v63, v0
	v_mov_b32_e32 v64, v0
	v_mov_b32_e32 v65, v0
	v_mov_b32_e32 v66, v0
	v_mov_b32_e32 v67, v0
	v_mov_b32_e32 v68, v0
	v_mov_b32_e32 v69, v0
	v_mov_b32_e32 v70, v0
	v_mov_b32_e32 v71, v0
	v_mov_b32_e32 v80, v0
	v_mov_b32_e32 v81, v0
	v_mov_b32_e32 v82, v0
	v_mov_b32_e32 v83, v0
	v_mov_b32_e32 v84, v0
	v_mov_b32_e32 v85, v0
	v_mov_b32_e32 v86, v0
	v_mov_b32_e32 v87, v0
	v_mov_b32_e32 v96, v0
	v_mov_b32_e32 v97, v0
	v_mov_b32_e32 v98, v0
	v_mov_b32_e32 v99, v0
	v_mov_b32_e32 v100, v0
	v_mov_b32_e32 v101, v0
	v_mov_b32_e32 v102, v0
	v_mov_b32_e32 v103, v0
	v_mov_b32_e32 v112, v0
	v_mov_b32_e32 v113, v0
	v_mov_b32_e32 v114, v0
	v_mov_b32_e32 v115, v0
	v_mov_b32_e32 v116, v0
	v_mov_b32_e32 v117, v0
	v_mov_b32_e32 v118, v0
	v_mov_b32_e32 v119, v0
	v_mov_b32_e32 v72, v0
	v_mov_b32_e32 v73, v0
	v_mov_b32_e32 v74, v0
	v_mov_b32_e32 v75, v0
	v_mov_b32_e32 v76, v0
	v_mov_b32_e32 v77, v0
	v_mov_b32_e32 v78, v0
	v_mov_b32_e32 v79, v0
	v_mov_b32_e32 v88, v0
	v_mov_b32_e32 v89, v0
	v_mov_b32_e32 v90, v0
	v_mov_b32_e32 v91, v0
	v_mov_b32_e32 v92, v0
	v_mov_b32_e32 v93, v0
	v_mov_b32_e32 v94, v0
	v_mov_b32_e32 v95, v0
	v_mov_b32_e32 v104, v0
	v_mov_b32_e32 v105, v0
	v_mov_b32_e32 v106, v0
	v_mov_b32_e32 v107, v0
	v_mov_b32_e32 v108, v0
	v_mov_b32_e32 v109, v0
	v_mov_b32_e32 v110, v0
	v_mov_b32_e32 v111, v0
	v_mov_b32_e32 v120, v0
	v_mov_b32_e32 v121, v0
	v_mov_b32_e32 v122, v0
	v_mov_b32_e32 v123, v0
	v_mov_b32_e32 v124, v0
	v_mov_b32_e32 v125, v0
	v_mov_b32_e32 v126, v0
	v_mov_b32_e32 v127, v0
	.p2alignl 6, 3212836864

; __device__ __forceinline__ void attn_phase(LAS unsigned char* lds, const bf16_t* QKVZ, const float* sinks, bf16_t* OG, int G, int bid, int tid) {
;     ...
;         const int g = wave >> 1, qh = wave & 1, h = kvh * 4 + g;
;         const float sink2 = sinks[h] * 1.4426950408889634f;
;         for (int mt = 0; mt < 4; ++mt) {
;             const int qo0 = qh * 64 + mt * 16;
;             const size_t row = (size_t)(b * T + n * 128 + qo0 + fr);
;             const bf16_t* qp = QKVZ + row * ATT_IN + h * 64 + fq * 8;
;             const bf16x8 q0 = *(const bf16x8*)qp, q1 = *(const bf16x8*)(qp + 32);
.Lmy_att_nosink:
	s_lshl_b32 s14, s12, 6
	s_ashr_i32 s15, s14, 31
	s_cmp_lg_u32 s0, 0
	s_cselect_b64 s[12:13], -1, 0
	s_lshl_b64 s[14:15], s[14:15], 1
	v_or_b32_e32 v33, s8, v99
	v_lshl_add_u64 v[80:81], v[78:79], 0, s[14:15]
	s_add_u32 s14, s4, s14
	s_mov_b32 s1, 0
	v_mov_b32_e32 v139, v119
	v_lshl_or_b32 v140, s0, 7, v33
	s_addc_u32 s15, s5, s15
	s_mov_b32 s8, s18
	s_cmp_lg_u32 s98, 0
	s_cbranch_scc1 .Lmy_att_t0
	v_mov_b64_e32 v[194:195], s[14:15]
	v_mad_i64_i32 v[196:197], s[26:27], v140, s22, v[194:195]
	v_lshl_add_u64 v[194:195], v[196:197], 0, v[72:73]
	global_load_dwordx4 v[186:189], v[194:195], off
	global_load_dwordx4 v[190:193], v[194:195], off offset:64
	s_waitcnt vmcnt(0)
	v_mul_f32_e32 v141, 0x3fb8aa3b, v32
	s_cmp_eq_u32 s54, 0x100
	s_cselect_b32 s98, 1, 0
	s_branch .Lmy_att_t0
	.p2alignl 6, 3212836864

; template <class Epi, class Sched, bool ALIGN_EPI = false, bool SP2 = false>
; __device__ __forceinline__ void gemm_phase(PG8_LAS unsigned char* lds, const Gemm g, const Sched& S, const Epi& E, const int tid_in) {
;     ...
;         const bool has_next = S.next(ui + 1, nxt);
;         const char* nA = has_next ? (const char*)g.asel(nxt.pn) + (size_t)nxt.pm * tstep : cA; const char* nB = has_next ? (const char*)g.Bt + (size_t)nxt.pn * tstep : cB;
;     ...
; #pragma unroll
;         for (int a = 0; a < 2; ++a)
; #pragma unroll
;             for (int b = 0; b < 2; ++b)
; #pragma unroll
;                 for (int m = 0; m < 4; ++m)
; #pragma unroll
;                     for (int n = 0; n < 2; ++n) acc[a][b][m][n] = (f32x4){0.f, 0.f, 0.f, 0.f};
;         cur = nxt; cA = nA; cB = nB; ++ui;
.LBB0_315:
	s_ashr_i32 s27, s26, 31
	s_lshl_b64 s[28:29], s[26:27], 19
	s_add_u32 s28, s33, s28
	s_addc_u32 s29, s40, s29
	s_and_b64 s[30:31], s[2:3], exec
	s_cselect_b32 s27, s29, s1
	s_cselect_b32 s58, s28, s0
	s_ashr_i32 s25, s24, 31
	s_lshl_b64 s[30:31], s[24:25], 19
	s_add_u32 s30, s41, s30
	s_addc_u32 s31, s42, s31
	s_and_b64 s[38:39], s[2:3], exec
	s_cselect_b32 s25, s31, s37
	s_cselect_b32 s59, s30, s36
	s_add_u32 s0, s0, 0x40080
	s_addc_u32 s1, s1, 0
	s_add_u32 s60, s36, 0x100
	v_mov_b32_e32 v0, 0
	s_addc_u32 s61, s37, 0
	s_mov_b32 s62, -2
	v_mov_b32_e32 v1, v0
	v_mov_b32_e32 v2, v0
	v_mov_b32_e32 v3, v0
	v_mov_b32_e32 v4, v0
	v_mov_b32_e32 v5, v0
	v_mov_b32_e32 v6, v0
	v_mov_b32_e32 v7, v0
	v_mov_b32_e32 v16, v0
	v_mov_b32_e32 v17, v0
	v_mov_b32_e32 v18, v0
	v_mov_b32_e32 v19, v0
	v_mov_b32_e32 v20, v0
	v_mov_b32_e32 v21, v0
	v_mov_b32_e32 v22, v0
	v_mov_b32_e32 v23, v0
	v_mov_b32_e32 v32, v0
	v_mov_b32_e32 v33, v0
	v_mov_b32_e32 v34, v0
	v_mov_b32_e32 v35, v0
	v_mov_b32_e32 v36, v0
	v_mov_b32_e32 v37, v0
	v_mov_b32_e32 v38, v0
	v_mov_b32_e32 v39, v0
	v_mov_b32_e32 v48, v0
	v_mov_b32_e32 v49, v0
	v_mov_b32_e32 v50, v0
	v_mov_b32_e32 v51, v0
	v_mov_b32_e32 v52, v0
	v_mov_b32_e32 v53, v0
	v_mov_b32_e32 v54, v0
	v_mov_b32_e32 v55, v0
	v_mov_b32_e32 v8, v0
	v_mov_b32_e32 v9, v0
	v_mov_b32_e32 v10, v0
	v_mov_b32_e32 v11, v0
	v_mov_b32_e32 v12, v0
	v_mov_b32_e32 v13, v0
	v_mov_b32_e32 v14, v0
	v_mov_b32_e32 v15, v0
	v_mov_b32_e32 v24, v0
	v_mov_b32_e32 v25, v0
	v_mov_b32_e32 v26, v0
	v_mov_b32_e32 v27, v0
	v_mov_b32_e32 v28, v0
	v_mov_b32_e32 v29, v0
	v_mov_b32_e32 v30, v0
	v_mov_b32_e32 v31, v0
	v_mov_b32_e32 v40, v0
	v_mov_b32_e32 v41, v0
	v_mov_b32_e32 v42, v0
	v_mov_b32_e32 v43, v0
	v_mov_b32_e32 v44, v0
	v_mov_b32_e32 v45, v0
	v_mov_b32_e32 v46, v0
	v_mov_b32_e32 v47, v0
	v_mov_b32_e32 v56, v0
	v_mov_b32_e32 v57, v0
	v_mov_b32_e32 v58, v0
	v_mov_b32_e32 v59, v0
	v_mov_b32_e32 v60, v0
	v_mov_b32_e32 v61, v0
	v_mov_b32_e32 v62, v0
	v_mov_b32_e32 v63, v0
	v_mov_b32_e32 v64, v0
	v_mov_b32_e32 v65, v0
	v_mov_b32_e32 v66, v0
	v_mov_b32_e32 v67, v0
	v_mov_b32_e32 v68, v0
	v_mov_b32_e32 v69, v0
	v_mov_b32_e32 v70, v0
	v_mov_b32_e32 v71, v0
	v_mov_b32_e32 v80, v0
	v_mov_b32_e32 v81, v0
	v_mov_b32_e32 v82, v0
	v_mov_b32_e32 v83, v0
	v_mov_b32_e32 v84, v0
	v_mov_b32_e32 v85, v0
	v_mov_b32_e32 v86, v0
	v_mov_b32_e32 v87, v0
	v_mov_b32_e32 v96, v0
	v_mov_b32_e32 v97, v0
	v_mov_b32_e32 v98, v0
	v_mov_b32_e32 v99, v0
	v_mov_b32_e32 v100, v0
	v_mov_b32_e32 v101, v0
	v_mov_b32_e32 v102, v0
	v_mov_b32_e32 v103, v0
	v_mov_b32_e32 v112, v0
	v_mov_b32_e32 v113, v0
	v_mov_b32_e32 v114, v0
	v_mov_b32_e32 v115, v0
	v_mov_b32_e32 v116, v0
	v_mov_b32_e32 v117, v0
	v_mov_b32_e32 v118, v0
	v_mov_b32_e32 v119, v0
	v_mov_b32_e32 v72, v0
	v_mov_b32_e32 v73, v0
	v_mov_b32_e32 v74, v0
	v_mov_b32_e32 v75, v0
	v_mov_b32_e32 v76, v0
	v_mov_b32_e32 v77, v0
	v_mov_b32_e32 v78, v0
	v_mov_b32_e32 v79, v0
	v_mov_b32_e32 v88, v0
	v_mov_b32_e32 v89, v0
	v_mov_b32_e32 v90, v0
	v_mov_b32_e32 v91, v0
	v_mov_b32_e32 v92, v0
	v_mov_b32_e32 v93, v0
	v_mov_b32_e32 v94, v0
	v_mov_b32_e32 v95, v0
	v_mov_b32_e32 v104, v0
	v_mov_b32_e32 v105, v0
	v_mov_b32_e32 v106, v0
	v_mov_b32_e32 v107, v0
	v_mov_b32_e32 v108, v0
	v_mov_b32_e32 v109, v0
	v_mov_b32_e32 v110, v0
	v_mov_b32_e32 v111, v0
	v_mov_b32_e32 v120, v0
	v_mov_b32_e32 v121, v0
	v_mov_b32_e32 v122, v0
	v_mov_b32_e32 v123, v0
	v_mov_b32_e32 v124, v0
	v_mov_b32_e32 v125, v0
	v_mov_b32_e32 v126, v0
	v_mov_b32_e32 v127, v0
	v_lshl_add_u32 v224, s34, 8, v150
	v_lshl_or_b32 v226, s57, 8, v152
	v_ashrrev_i32_e32 v225, 31, v224
	v_ashrrev_i32_e32 v227, 31, v226
	v_lshlrev_b64 v[224:225], 10, v[224:225]
	v_lshl_add_u64 v[224:225], v[224:225], 0, v[226:227]
	v_lshl_add_u64 v[224:225], v[224:225], 2, s[6:7]
	.p2alignl 6, 3212836864

; template <class Epi, class Sched, bool ALIGN_EPI = false, bool SP2 = false>
; __device__ __forceinline__ void gemm_phase(PG8_LAS unsigned char* lds, const Gemm g, const Sched& S, const Epi& E, const int tid_in) {
;     ...
;         const bool has_next = S.next(ui + 1, nxt);
;         const char* nA = has_next ? (const char*)g.asel(nxt.pn) + (size_t)nxt.pm * tstep : cA; const char* nB = has_next ? (const char*)g.Bt + (size_t)nxt.pn * tstep : cB;
;     ...
; #pragma unroll
;         for (int a = 0; a < 2; ++a)
; #pragma unroll
;             for (int b = 0; b < 2; ++b)
; #pragma unroll
;                 for (int m = 0; m < 4; ++m)
; #pragma unroll
;                     for (int n = 0; n < 2; ++n) acc[a][b][m][n] = (f32x4){0.f, 0.f, 0.f, 0.f};
;         cur = nxt; cA = nA; cB = nB; ++ui;
.LBB0_390:
	s_ashr_i32 s29, s28, 31
	s_lshl_b64 s[30:31], s[28:29], 19
	s_add_u32 s30, s6, s30
	s_addc_u32 s31, s7, s31
	s_and_b64 s[34:35], s[2:3], exec
	s_cselect_b32 s29, s31, s1
	s_cselect_b32 s58, s30, s0
	s_ashr_i32 s27, s26, 31
	s_lshl_b64 s[34:35], s[26:27], 19
	s_add_u32 s34, s33, s34
	s_addc_u32 s35, s42, s35
	s_and_b64 s[40:41], s[2:3], exec
	s_cselect_b32 s27, s35, s39
	s_cselect_b32 s59, s34, s38
	s_add_u32 s0, s0, 0x40080
	s_addc_u32 s1, s1, 0
	s_add_u32 s60, s38, 0x100
	v_mov_b32_e32 v0, 0
	s_addc_u32 s61, s39, 0
	s_mov_b32 s62, -2
	v_mov_b32_e32 v1, v0
	v_mov_b32_e32 v2, v0
	v_mov_b32_e32 v3, v0
	v_mov_b32_e32 v4, v0
	v_mov_b32_e32 v5, v0
	v_mov_b32_e32 v6, v0
	v_mov_b32_e32 v7, v0
	v_mov_b32_e32 v16, v0
	v_mov_b32_e32 v17, v0
	v_mov_b32_e32 v18, v0
	v_mov_b32_e32 v19, v0
	v_mov_b32_e32 v20, v0
	v_mov_b32_e32 v21, v0
	v_mov_b32_e32 v22, v0
	v_mov_b32_e32 v23, v0
	v_mov_b32_e32 v32, v0
	v_mov_b32_e32 v33, v0
	v_mov_b32_e32 v34, v0
	v_mov_b32_e32 v35, v0
	v_mov_b32_e32 v36, v0
	v_mov_b32_e32 v37, v0
	v_mov_b32_e32 v38, v0
	v_mov_b32_e32 v39, v0
	v_mov_b32_e32 v48, v0
	v_mov_b32_e32 v49, v0
	v_mov_b32_e32 v50, v0
	v_mov_b32_e32 v51, v0
	v_mov_b32_e32 v52, v0
	v_mov_b32_e32 v53, v0
	v_mov_b32_e32 v54, v0
	v_mov_b32_e32 v55, v0
	v_mov_b32_e32 v8, v0
	v_mov_b32_e32 v9, v0
	v_mov_b32_e32 v10, v0
	v_mov_b32_e32 v11, v0
	v_mov_b32_e32 v12, v0
	v_mov_b32_e32 v13, v0
	v_mov_b32_e32 v14, v0
	v_mov_b32_e32 v15, v0
	v_mov_b32_e32 v24, v0
	v_mov_b32_e32 v25, v0
	v_mov_b32_e32 v26, v0
	v_mov_b32_e32 v27, v0
	v_mov_b32_e32 v28, v0
	v_mov_b32_e32 v29, v0
	v_mov_b32_e32 v30, v0
	v_mov_b32_e32 v31, v0
	v_mov_b32_e32 v40, v0
	v_mov_b32_e32 v41, v0
	v_mov_b32_e32 v42, v0
	v_mov_b32_e32 v43, v0
	v_mov_b32_e32 v44, v0
	v_mov_b32_e32 v45, v0
	v_mov_b32_e32 v46, v0
	v_mov_b32_e32 v47, v0
	v_mov_b32_e32 v56, v0
	v_mov_b32_e32 v57, v0
	v_mov_b32_e32 v58, v0
	v_mov_b32_e32 v59, v0
	v_mov_b32_e32 v60, v0
	v_mov_b32_e32 v61, v0
	v_mov_b32_e32 v62, v0
	v_mov_b32_e32 v63, v0
	v_mov_b32_e32 v64, v0
	v_mov_b32_e32 v65, v0
	v_mov_b32_e32 v66, v0
	v_mov_b32_e32 v67, v0
	v_mov_b32_e32 v68, v0
	v_mov_b32_e32 v69, v0
	v_mov_b32_e32 v70, v0
	v_mov_b32_e32 v71, v0
	v_mov_b32_e32 v80, v0
	v_mov_b32_e32 v81, v0
	v_mov_b32_e32 v82, v0
	v_mov_b32_e32 v83, v0
	v_mov_b32_e32 v84, v0
	v_mov_b32_e32 v85, v0
	v_mov_b32_e32 v86, v0
	v_mov_b32_e32 v87, v0
	v_mov_b32_e32 v96, v0
	v_mov_b32_e32 v97, v0
	v_mov_b32_e32 v98, v0
	v_mov_b32_e32 v99, v0
	v_mov_b32_e32 v100, v0
	v_mov_b32_e32 v101, v0
	v_mov_b32_e32 v102, v0
	v_mov_b32_e32 v103, v0
	v_mov_b32_e32 v112, v0
	v_mov_b32_e32 v113, v0
	v_mov_b32_e32 v114, v0
	v_mov_b32_e32 v115, v0
	v_mov_b32_e32 v116, v0
	v_mov_b32_e32 v117, v0
	v_mov_b32_e32 v118, v0
	v_mov_b32_e32 v119, v0
	v_mov_b32_e32 v72, v0
	v_mov_b32_e32 v73, v0
	v_mov_b32_e32 v74, v0
	v_mov_b32_e32 v75, v0
	v_mov_b32_e32 v76, v0
	v_mov_b32_e32 v77, v0
	v_mov_b32_e32 v78, v0
	v_mov_b32_e32 v79, v0
	v_mov_b32_e32 v88, v0
	v_mov_b32_e32 v89, v0
	v_mov_b32_e32 v90, v0
	v_mov_b32_e32 v91, v0
	v_mov_b32_e32 v92, v0
	v_mov_b32_e32 v93, v0
	v_mov_b32_e32 v94, v0
	v_mov_b32_e32 v95, v0
	v_mov_b32_e32 v104, v0
	v_mov_b32_e32 v105, v0
	v_mov_b32_e32 v106, v0
	v_mov_b32_e32 v107, v0
	v_mov_b32_e32 v108, v0
	v_mov_b32_e32 v109, v0
	v_mov_b32_e32 v110, v0
	v_mov_b32_e32 v111, v0
	v_mov_b32_e32 v120, v0
	v_mov_b32_e32 v121, v0
	v_mov_b32_e32 v122, v0
	v_mov_b32_e32 v123, v0
	v_mov_b32_e32 v124, v0
	v_mov_b32_e32 v125, v0
	v_mov_b32_e32 v126, v0
	v_mov_b32_e32 v127, v0
	.p2alignl 6, 3212836864

; template <class Epi, class Sched, bool ALIGN_EPI = false, bool SP2 = false>
; __device__ __forceinline__ void gemm_phase(PG8_LAS unsigned char* lds, const Gemm g, const Sched& S, const Epi& E, const int tid_in) {
;     ...
;         const bool has_next = S.next(ui + 1, nxt);
;         const char* nA = has_next ? (const char*)g.asel(nxt.pn) + (size_t)nxt.pm * tstep : cA; const char* nB = has_next ? (const char*)g.Bt + (size_t)nxt.pn * tstep : cB;
;     ...
; #pragma unroll
;         for (int a = 0; a < 2; ++a)
; #pragma unroll
;             for (int b = 0; b < 2; ++b)
; #pragma unroll
;                 for (int m = 0; m < 4; ++m)
; #pragma unroll
;                     for (int n = 0; n < 2; ++n) acc[a][b][m][n] = (f32x4){0.f, 0.f, 0.f, 0.f};
;         cur = nxt; cA = nA; cB = nB; ++ui;
.LBB0_534:
	s_cmp_lt_i32 s26, 4
	s_cselect_b32 s27, s46, s50
	s_cselect_b32 s34, s45, s49
	s_ashr_i32 s29, s28, 31
	s_lshl_b64 s[30:31], s[28:29], 19
	s_add_u32 s30, s34, s30
	s_addc_u32 s31, s27, s31
	s_and_b64 s[34:35], s[2:3], exec
	s_cselect_b32 s29, s31, s1
	s_cselect_b32 s69, s30, s0
	s_ashr_i32 s27, s26, 31
	s_lshl_b64 s[34:35], s[26:27], 19
	s_add_u32 s34, s47, s34
	s_addc_u32 s35, s48, s35
	s_and_b64 s[40:41], s[2:3], exec
	s_cselect_b32 s27, s35, s39
	s_cselect_b32 s70, s34, s38
	s_add_u32 s0, s0, 0x40080
	s_addc_u32 s1, s1, 0
	s_add_u32 s71, s38, 0x100
	v_mov_b32_e32 v0, 0
	s_addc_u32 s72, s39, 0
	s_mov_b32 s73, -2
	v_mov_b32_e32 v1, v0
	v_mov_b32_e32 v2, v0
	v_mov_b32_e32 v3, v0
	v_mov_b32_e32 v4, v0
	v_mov_b32_e32 v5, v0
	v_mov_b32_e32 v6, v0
	v_mov_b32_e32 v7, v0
	v_mov_b32_e32 v8, v0
	v_mov_b32_e32 v9, v0
	v_mov_b32_e32 v10, v0
	v_mov_b32_e32 v11, v0
	v_mov_b32_e32 v16, v0
	v_mov_b32_e32 v17, v0
	v_mov_b32_e32 v18, v0
	v_mov_b32_e32 v19, v0
	v_mov_b32_e32 v24, v0
	v_mov_b32_e32 v25, v0
	v_mov_b32_e32 v26, v0
	v_mov_b32_e32 v27, v0
	v_mov_b32_e32 v32, v0
	v_mov_b32_e32 v33, v0
	v_mov_b32_e32 v34, v0
	v_mov_b32_e32 v35, v0
	v_mov_b32_e32 v40, v0
	v_mov_b32_e32 v41, v0
	v_mov_b32_e32 v42, v0
	v_mov_b32_e32 v43, v0
	v_mov_b32_e32 v48, v0
	v_mov_b32_e32 v49, v0
	v_mov_b32_e32 v50, v0
	v_mov_b32_e32 v51, v0
	v_mov_b32_e32 v12, v0
	v_mov_b32_e32 v13, v0
	v_mov_b32_e32 v14, v0
	v_mov_b32_e32 v15, v0
	v_mov_b32_e32 v20, v0
	v_mov_b32_e32 v21, v0
	v_mov_b32_e32 v22, v0
	v_mov_b32_e32 v23, v0
	v_mov_b32_e32 v28, v0
	v_mov_b32_e32 v29, v0
	v_mov_b32_e32 v30, v0
	v_mov_b32_e32 v31, v0
	v_mov_b32_e32 v36, v0
	v_mov_b32_e32 v37, v0
	v_mov_b32_e32 v38, v0
	v_mov_b32_e32 v39, v0
	v_mov_b32_e32 v44, v0
	v_mov_b32_e32 v45, v0
	v_mov_b32_e32 v46, v0
	v_mov_b32_e32 v47, v0
	v_mov_b32_e32 v52, v0
	v_mov_b32_e32 v53, v0
	v_mov_b32_e32 v54, v0
	v_mov_b32_e32 v55, v0
	v_mov_b32_e32 v56, v0
	v_mov_b32_e32 v57, v0
	v_mov_b32_e32 v58, v0
	v_mov_b32_e32 v59, v0
	v_mov_b32_e32 v60, v0
	v_mov_b32_e32 v61, v0
	v_mov_b32_e32 v62, v0
	v_mov_b32_e32 v63, v0
	v_mov_b32_e32 v64, v0
	v_mov_b32_e32 v65, v0
	v_mov_b32_e32 v66, v0
	v_mov_b32_e32 v67, v0
	v_mov_b32_e32 v68, v0
	v_mov_b32_e32 v69, v0
	v_mov_b32_e32 v70, v0
	v_mov_b32_e32 v71, v0
	v_mov_b32_e32 v72, v0
	v_mov_b32_e32 v73, v0
	v_mov_b32_e32 v74, v0
	v_mov_b32_e32 v75, v0
	v_mov_b32_e32 v80, v0
	v_mov_b32_e32 v81, v0
	v_mov_b32_e32 v82, v0
	v_mov_b32_e32 v83, v0
	v_mov_b32_e32 v88, v0
	v_mov_b32_e32 v89, v0
	v_mov_b32_e32 v90, v0
	v_mov_b32_e32 v91, v0
	v_mov_b32_e32 v96, v0
	v_mov_b32_e32 v97, v0
	v_mov_b32_e32 v98, v0
	v_mov_b32_e32 v99, v0
	v_mov_b32_e32 v104, v0
	v_mov_b32_e32 v105, v0
	v_mov_b32_e32 v106, v0
	v_mov_b32_e32 v107, v0
	v_mov_b32_e32 v112, v0
	v_mov_b32_e32 v113, v0
	v_mov_b32_e32 v114, v0
	v_mov_b32_e32 v115, v0
	v_mov_b32_e32 v76, v0
	v_mov_b32_e32 v77, v0
	v_mov_b32_e32 v78, v0
	v_mov_b32_e32 v79, v0
	v_mov_b32_e32 v84, v0
	v_mov_b32_e32 v85, v0
	v_mov_b32_e32 v86, v0
	v_mov_b32_e32 v87, v0
	v_mov_b32_e32 v92, v0
	v_mov_b32_e32 v93, v0
	v_mov_b32_e32 v94, v0
	v_mov_b32_e32 v95, v0
	v_mov_b32_e32 v100, v0
	v_mov_b32_e32 v101, v0
	v_mov_b32_e32 v102, v0
	v_mov_b32_e32 v103, v0
	v_mov_b32_e32 v108, v0
	v_mov_b32_e32 v109, v0
	v_mov_b32_e32 v110, v0
	v_mov_b32_e32 v111, v0
	v_mov_b32_e32 v116, v0
	v_mov_b32_e32 v117, v0
	v_mov_b32_e32 v118, v0
	v_mov_b32_e32 v119, v0
	v_mov_b32_e32 v120, v0
	v_mov_b32_e32 v121, v0
	v_mov_b32_e32 v122, v0
	v_mov_b32_e32 v123, v0
	v_mov_b32_e32 v124, v0
	v_mov_b32_e32 v125, v0
	v_mov_b32_e32 v126, v0
	v_mov_b32_e32 v127, v0
	.p2alignl 6, 3212836864

; template <class Epi, class Sched, bool ALIGN_EPI = false, bool SP2 = false>
; __device__ __forceinline__ void gemm_phase(PG8_LAS unsigned char* lds, const Gemm g, const Sched& S, const Epi& E, const int tid_in) {
;     ...
;         const bool has_next = S.next(ui + 1, nxt);
;         const char* nA = has_next ? (const char*)g.asel(nxt.pn) + (size_t)nxt.pm * tstep : cA; const char* nB = has_next ? (const char*)g.Bt + (size_t)nxt.pn * tstep : cB;
;     ...
; #pragma unroll
;         for (int a = 0; a < 2; ++a)
; #pragma unroll
;             for (int b = 0; b < 2; ++b)
; #pragma unroll
;                 for (int m = 0; m < 4; ++m)
; #pragma unroll
;                     for (int n = 0; n < 2; ++n) acc[a][b][m][n] = (f32x4){0.f, 0.f, 0.f, 0.f};
;         cur = nxt; cA = nA; cB = nB; ++ui;
.LBB0_554:
	s_ashr_i32 s25, s24, 31
	s_lshl_b64 s[26:27], s[24:25], 19
	s_add_u32 s23, s38, s26
	s_addc_u32 s25, s39, s27
	s_and_b64 s[26:27], s[2:3], exec
	s_cselect_b32 s27, s25, s1
	s_cselect_b32 s26, s23, s0
	s_ashr_i32 s23, s22, 31
	s_lshl_b64 s[28:29], s[22:23], 19
	s_add_u32 s28, s40, s28
	s_addc_u32 s29, s41, s29
	s_and_b64 s[36:37], s[2:3], exec
	s_cselect_b32 s23, s29, s35
	s_cselect_b32 s25, s28, s34
	s_add_u32 s0, s0, 0x40080
	s_addc_u32 s1, s1, 0
	s_add_u32 s59, s34, 0x100
	v_mov_b32_e32 v0, 0
	s_addc_u32 s60, s35, 0
	s_mov_b32 s61, -2
	v_mov_b32_e32 v1, v0
	v_mov_b32_e32 v2, v0
	v_mov_b32_e32 v3, v0
	v_mov_b32_e32 v4, v0
	v_mov_b32_e32 v5, v0
	v_mov_b32_e32 v6, v0
	v_mov_b32_e32 v7, v0
	v_mov_b32_e32 v8, v0
	v_mov_b32_e32 v9, v0
	v_mov_b32_e32 v10, v0
	v_mov_b32_e32 v11, v0
	v_mov_b32_e32 v16, v0
	v_mov_b32_e32 v17, v0
	v_mov_b32_e32 v18, v0
	v_mov_b32_e32 v19, v0
	v_mov_b32_e32 v24, v0
	v_mov_b32_e32 v25, v0
	v_mov_b32_e32 v26, v0
	v_mov_b32_e32 v27, v0
	v_mov_b32_e32 v32, v0
	v_mov_b32_e32 v33, v0
	v_mov_b32_e32 v34, v0
	v_mov_b32_e32 v35, v0
	v_mov_b32_e32 v40, v0
	v_mov_b32_e32 v41, v0
	v_mov_b32_e32 v42, v0
	v_mov_b32_e32 v43, v0
	v_mov_b32_e32 v48, v0
	v_mov_b32_e32 v49, v0
	v_mov_b32_e32 v50, v0
	v_mov_b32_e32 v51, v0
	v_mov_b32_e32 v12, v0
	v_mov_b32_e32 v13, v0
	v_mov_b32_e32 v14, v0
	v_mov_b32_e32 v15, v0
	v_mov_b32_e32 v20, v0
	v_mov_b32_e32 v21, v0
	v_mov_b32_e32 v22, v0
	v_mov_b32_e32 v23, v0
	v_mov_b32_e32 v28, v0
	v_mov_b32_e32 v29, v0
	v_mov_b32_e32 v30, v0
	v_mov_b32_e32 v31, v0
	v_mov_b32_e32 v36, v0
	v_mov_b32_e32 v37, v0
	v_mov_b32_e32 v38, v0
	v_mov_b32_e32 v39, v0
	v_mov_b32_e32 v44, v0
	v_mov_b32_e32 v45, v0
	v_mov_b32_e32 v46, v0
	v_mov_b32_e32 v47, v0
	v_mov_b32_e32 v52, v0
	v_mov_b32_e32 v53, v0
	v_mov_b32_e32 v54, v0
	v_mov_b32_e32 v55, v0
	v_mov_b32_e32 v56, v0
	v_mov_b32_e32 v57, v0
	v_mov_b32_e32 v58, v0
	v_mov_b32_e32 v59, v0
	v_mov_b32_e32 v60, v0
	v_mov_b32_e32 v61, v0
	v_mov_b32_e32 v62, v0
	v_mov_b32_e32 v63, v0
	v_mov_b32_e32 v64, v0
	v_mov_b32_e32 v65, v0
	v_mov_b32_e32 v66, v0
	v_mov_b32_e32 v67, v0
	v_mov_b32_e32 v68, v0
	v_mov_b32_e32 v69, v0
	v_mov_b32_e32 v70, v0
	v_mov_b32_e32 v71, v0
	v_mov_b32_e32 v72, v0
	v_mov_b32_e32 v73, v0
	v_mov_b32_e32 v74, v0
	v_mov_b32_e32 v75, v0
	v_mov_b32_e32 v80, v0
	v_mov_b32_e32 v81, v0
	v_mov_b32_e32 v82, v0
	v_mov_b32_e32 v83, v0
	v_mov_b32_e32 v88, v0
	v_mov_b32_e32 v89, v0
	v_mov_b32_e32 v90, v0
	v_mov_b32_e32 v91, v0
	v_mov_b32_e32 v96, v0
	v_mov_b32_e32 v97, v0
	v_mov_b32_e32 v98, v0
	v_mov_b32_e32 v99, v0
	v_mov_b32_e32 v104, v0
	v_mov_b32_e32 v105, v0
	v_mov_b32_e32 v106, v0
	v_mov_b32_e32 v107, v0
	v_mov_b32_e32 v112, v0
	v_mov_b32_e32 v113, v0
	v_mov_b32_e32 v114, v0
	v_mov_b32_e32 v115, v0
	v_mov_b32_e32 v76, v0
	v_mov_b32_e32 v77, v0
	v_mov_b32_e32 v78, v0
	v_mov_b32_e32 v79, v0
	v_mov_b32_e32 v84, v0
	v_mov_b32_e32 v85, v0
	v_mov_b32_e32 v86, v0
	v_mov_b32_e32 v87, v0
	v_mov_b32_e32 v92, v0
	v_mov_b32_e32 v93, v0
	v_mov_b32_e32 v94, v0
	v_mov_b32_e32 v95, v0
	v_mov_b32_e32 v100, v0
	v_mov_b32_e32 v101, v0
	v_mov_b32_e32 v102, v0
	v_mov_b32_e32 v103, v0
	v_mov_b32_e32 v108, v0
	v_mov_b32_e32 v109, v0
	v_mov_b32_e32 v110, v0
	v_mov_b32_e32 v111, v0
	v_mov_b32_e32 v116, v0
	v_mov_b32_e32 v117, v0
	v_mov_b32_e32 v118, v0
	v_mov_b32_e32 v119, v0
	v_mov_b32_e32 v120, v0
	v_mov_b32_e32 v121, v0
	v_mov_b32_e32 v122, v0
	v_mov_b32_e32 v123, v0
	v_mov_b32_e32 v124, v0
	v_mov_b32_e32 v125, v0
	v_mov_b32_e32 v126, v0
	v_mov_b32_e32 v127, v0
	.p2alignl 6, 3212836864

; template <class Epi, class Sched, bool ALIGN_EPI = false, bool SP2 = false>
; __device__ __forceinline__ void gemm_phase(PG8_LAS unsigned char* lds, const Gemm g, const Sched& S, const Epi& E, const int tid_in) {
;     ...
;         const bool has_next = S.next(ui + 1, nxt);
;         const char* nA = has_next ? (const char*)g.asel(nxt.pn) + (size_t)nxt.pm * tstep : cA; const char* nB = has_next ? (const char*)g.Bt + (size_t)nxt.pn * tstep : cB;
;     ...
; #pragma unroll
;         for (int a = 0; a < 2; ++a)
; #pragma unroll
;             for (int b = 0; b < 2; ++b)
; #pragma unroll
;                 for (int m = 0; m < 4; ++m)
; #pragma unroll
;                     for (int n = 0; n < 2; ++n) acc[a][b][m][n] = (f32x4){0.f, 0.f, 0.f, 0.f};
;         cur = nxt; cA = nA; cB = nB; ++ui;
.LBB0_738:
	s_cmp_lt_i32 s20, 4
	s_cselect_b32 s21, s36, s40
	s_cselect_b32 s26, s33, s39
	s_ashr_i32 s23, s22, 31
	s_lshl_b64 s[24:25], s[22:23], 19
	s_add_u32 s24, s26, s24
	s_addc_u32 s25, s21, s25
	s_and_b64 s[26:27], s[2:3], exec
	s_cselect_b32 s23, s25, s1
	s_cselect_b32 s64, s24, s0
	s_ashr_i32 s21, s20, 31
	s_lshl_b64 s[26:27], s[20:21], 19
	s_add_u32 s26, s37, s26
	s_addc_u32 s27, s38, s27
	s_and_b64 s[34:35], s[2:3], exec
	s_cselect_b32 s21, s27, s31
	s_cselect_b32 s65, s26, s30
	s_add_u32 s0, s0, 0x40080
	s_addc_u32 s1, s1, 0
	s_add_u32 s66, s30, 0x100
	v_mov_b32_e32 v0, 0
	s_addc_u32 s67, s31, 0
	s_mov_b32 s68, -2
	v_mov_b32_e32 v1, v0
	v_mov_b32_e32 v2, v0
	v_mov_b32_e32 v3, v0
	v_mov_b32_e32 v4, v0
	v_mov_b32_e32 v5, v0
	v_mov_b32_e32 v6, v0
	v_mov_b32_e32 v7, v0
	v_mov_b32_e32 v8, v0
	v_mov_b32_e32 v9, v0
	v_mov_b32_e32 v10, v0
	v_mov_b32_e32 v11, v0
	v_mov_b32_e32 v16, v0
	v_mov_b32_e32 v17, v0
	v_mov_b32_e32 v18, v0
	v_mov_b32_e32 v19, v0
	v_mov_b32_e32 v24, v0
	v_mov_b32_e32 v25, v0
	v_mov_b32_e32 v26, v0
	v_mov_b32_e32 v27, v0
	v_mov_b32_e32 v32, v0
	v_mov_b32_e32 v33, v0
	v_mov_b32_e32 v34, v0
	v_mov_b32_e32 v35, v0
	v_mov_b32_e32 v40, v0
	v_mov_b32_e32 v41, v0
	v_mov_b32_e32 v42, v0
	v_mov_b32_e32 v43, v0
	v_mov_b32_e32 v48, v0
	v_mov_b32_e32 v49, v0
	v_mov_b32_e32 v50, v0
	v_mov_b32_e32 v51, v0
	v_mov_b32_e32 v12, v0
	v_mov_b32_e32 v13, v0
	v_mov_b32_e32 v14, v0
	v_mov_b32_e32 v15, v0
	v_mov_b32_e32 v20, v0
	v_mov_b32_e32 v21, v0
	v_mov_b32_e32 v22, v0
	v_mov_b32_e32 v23, v0
	v_mov_b32_e32 v28, v0
	v_mov_b32_e32 v29, v0
	v_mov_b32_e32 v30, v0
	v_mov_b32_e32 v31, v0
	v_mov_b32_e32 v36, v0
	v_mov_b32_e32 v37, v0
	v_mov_b32_e32 v38, v0
	v_mov_b32_e32 v39, v0
	v_mov_b32_e32 v44, v0
	v_mov_b32_e32 v45, v0
	v_mov_b32_e32 v46, v0
	v_mov_b32_e32 v47, v0
	v_mov_b32_e32 v52, v0
	v_mov_b32_e32 v53, v0
	v_mov_b32_e32 v54, v0
	v_mov_b32_e32 v55, v0
	v_mov_b32_e32 v56, v0
	v_mov_b32_e32 v57, v0
	v_mov_b32_e32 v58, v0
	v_mov_b32_e32 v59, v0
	v_mov_b32_e32 v60, v0
	v_mov_b32_e32 v61, v0
	v_mov_b32_e32 v62, v0
	v_mov_b32_e32 v63, v0
	v_mov_b32_e32 v64, v0
	v_mov_b32_e32 v65, v0
	v_mov_b32_e32 v66, v0
	v_mov_b32_e32 v67, v0
	v_mov_b32_e32 v68, v0
	v_mov_b32_e32 v69, v0
	v_mov_b32_e32 v70, v0
	v_mov_b32_e32 v71, v0
	v_mov_b32_e32 v72, v0
	v_mov_b32_e32 v73, v0
	v_mov_b32_e32 v74, v0
	v_mov_b32_e32 v75, v0
	v_mov_b32_e32 v80, v0
	v_mov_b32_e32 v81, v0
	v_mov_b32_e32 v82, v0
	v_mov_b32_e32 v83, v0
	v_mov_b32_e32 v88, v0
	v_mov_b32_e32 v89, v0
	v_mov_b32_e32 v90, v0
	v_mov_b32_e32 v91, v0
	v_mov_b32_e32 v96, v0
	v_mov_b32_e32 v97, v0
	v_mov_b32_e32 v98, v0
	v_mov_b32_e32 v99, v0
	v_mov_b32_e32 v104, v0
	v_mov_b32_e32 v105, v0
	v_mov_b32_e32 v106, v0
	v_mov_b32_e32 v107, v0
	v_mov_b32_e32 v112, v0
	v_mov_b32_e32 v113, v0
	v_mov_b32_e32 v114, v0
	v_mov_b32_e32 v115, v0
	v_mov_b32_e32 v76, v0
	v_mov_b32_e32 v77, v0
	v_mov_b32_e32 v78, v0
	v_mov_b32_e32 v79, v0
	v_mov_b32_e32 v84, v0
	v_mov_b32_e32 v85, v0
	v_mov_b32_e32 v86, v0
	v_mov_b32_e32 v87, v0
	v_mov_b32_e32 v92, v0
	v_mov_b32_e32 v93, v0
	v_mov_b32_e32 v94, v0
	v_mov_b32_e32 v95, v0
	v_mov_b32_e32 v100, v0
	v_mov_b32_e32 v101, v0
	v_mov_b32_e32 v102, v0
	v_mov_b32_e32 v103, v0
	v_mov_b32_e32 v108, v0
	v_mov_b32_e32 v109, v0
	v_mov_b32_e32 v110, v0
	v_mov_b32_e32 v111, v0
	v_mov_b32_e32 v116, v0
	v_mov_b32_e32 v117, v0
	v_mov_b32_e32 v118, v0
	v_mov_b32_e32 v119, v0
	v_mov_b32_e32 v120, v0
	v_mov_b32_e32 v121, v0
	v_mov_b32_e32 v122, v0
	v_mov_b32_e32 v123, v0
	v_mov_b32_e32 v124, v0
	v_mov_b32_e32 v125, v0
	v_mov_b32_e32 v126, v0
	v_mov_b32_e32 v127, v0
	.p2alignl 6, 3212836864

; __device__ __forceinline__ void scan_phase(LAS unsigned char* lds, const bf16_t* R, const bf16_t* Kb, const bf16_t* V, const bf16_t* WA, const float* k_k, const float* k_a, bf16_t* Y, int G, int bid, int tid) {
;     ...
;             __syncthreads();
;         }
.LBB0_915:
	s_add_u32 s60, s60, 0x8000
	s_addc_u32 s61, s61, 0
	s_mov_b64 s[0:1], 0x10000
	v_lshl_add_u64 v[144:145], v[144:145], 0, s[0:1]
	s_cmp_eq_u32 s60, 0x808000
	s_mov_b32 s63, s62
	s_waitcnt lgkmcnt(0)
	s_barrier
	s_cbranch_scc1 .LBB0_876
	.p2alignl 6, 3212836864

; template <class Epi, class Sched, bool ALIGN_EPI = false, bool SP2 = false>
; __device__ __forceinline__ void gemm_phase(PG8_LAS unsigned char* lds, const Gemm g, const Sched& S, const Epi& E, const int tid_in) {
;     ...
;         const bool has_next = S.next(ui + 1, nxt);
;         const char* nA = has_next ? (const char*)g.asel(nxt.pn) + (size_t)nxt.pm * tstep : cA; const char* nB = has_next ? (const char*)g.Bt + (size_t)nxt.pn * tstep : cB;
;     ...
; #pragma unroll
;         for (int a = 0; a < 2; ++a)
; #pragma unroll
;             for (int b = 0; b < 2; ++b)
; #pragma unroll
;                 for (int m = 0; m < 4; ++m)
; #pragma unroll
;                     for (int n = 0; n < 2; ++n) acc[a][b][m][n] = (f32x4){0.f, 0.f, 0.f, 0.f};
;         cur = nxt; cA = nA; cB = nB; ++ui;
.LBB0_1079:
	s_ashr_i32 s35, s34, 31
	s_lshl_b64 s[36:37], s[34:35], 19
	s_add_u32 s36, s48, s36
	s_addc_u32 s37, s49, s37
	s_and_b64 s[38:39], s[2:3], exec
	s_cselect_b32 s35, s37, s1
	s_cselect_b32 s66, s36, s0
	s_ashr_i32 s31, s30, 31
	s_lshl_b64 s[38:39], s[30:31], 19
	s_add_u32 s38, s52, s38
	s_addc_u32 s39, s53, s39
	s_and_b64 s[44:45], s[2:3], exec
	s_cselect_b32 s31, s39, s43
	s_cselect_b32 s67, s38, s42
	s_add_u32 s0, s0, 0x40080
	s_addc_u32 s1, s1, 0
	s_add_u32 s68, s42, 0x100
	v_mov_b32_e32 v0, 0
	s_addc_u32 s69, s43, 0
	s_mov_b32 s70, -2
	v_mov_b32_e32 v1, v0
	v_mov_b32_e32 v2, v0
	v_mov_b32_e32 v3, v0
	v_mov_b32_e32 v4, v0
	v_mov_b32_e32 v5, v0
	v_mov_b32_e32 v6, v0
	v_mov_b32_e32 v7, v0
	v_mov_b32_e32 v12, v0
	v_mov_b32_e32 v13, v0
	v_mov_b32_e32 v14, v0
	v_mov_b32_e32 v15, v0
	v_mov_b32_e32 v16, v0
	v_mov_b32_e32 v17, v0
	v_mov_b32_e32 v18, v0
	v_mov_b32_e32 v19, v0
	v_mov_b32_e32 v28, v0
	v_mov_b32_e32 v29, v0
	v_mov_b32_e32 v30, v0
	v_mov_b32_e32 v31, v0
	v_mov_b32_e32 v32, v0
	v_mov_b32_e32 v33, v0
	v_mov_b32_e32 v34, v0
	v_mov_b32_e32 v35, v0
	v_mov_b32_e32 v44, v0
	v_mov_b32_e32 v45, v0
	v_mov_b32_e32 v46, v0
	v_mov_b32_e32 v47, v0
	v_mov_b32_e32 v48, v0
	v_mov_b32_e32 v49, v0
	v_mov_b32_e32 v50, v0
	v_mov_b32_e32 v51, v0
	v_mov_b32_e32 v8, v0
	v_mov_b32_e32 v9, v0
	v_mov_b32_e32 v10, v0
	v_mov_b32_e32 v11, v0
	v_mov_b32_e32 v20, v0
	v_mov_b32_e32 v21, v0
	v_mov_b32_e32 v22, v0
	v_mov_b32_e32 v23, v0
	v_mov_b32_e32 v24, v0
	v_mov_b32_e32 v25, v0
	v_mov_b32_e32 v26, v0
	v_mov_b32_e32 v27, v0
	v_mov_b32_e32 v36, v0
	v_mov_b32_e32 v37, v0
	v_mov_b32_e32 v38, v0
	v_mov_b32_e32 v39, v0
	v_mov_b32_e32 v40, v0
	v_mov_b32_e32 v41, v0
	v_mov_b32_e32 v42, v0
	v_mov_b32_e32 v43, v0
	v_mov_b32_e32 v52, v0
	v_mov_b32_e32 v53, v0
	v_mov_b32_e32 v54, v0
	v_mov_b32_e32 v55, v0
	v_mov_b32_e32 v56, v0
	v_mov_b32_e32 v57, v0
	v_mov_b32_e32 v58, v0
	v_mov_b32_e32 v59, v0
	v_mov_b32_e32 v60, v0
	v_mov_b32_e32 v61, v0
	v_mov_b32_e32 v62, v0
	v_mov_b32_e32 v63, v0
	v_mov_b32_e32 v64, v0
	v_mov_b32_e32 v65, v0
	v_mov_b32_e32 v66, v0
	v_mov_b32_e32 v67, v0
	v_mov_b32_e32 v68, v0
	v_mov_b32_e32 v69, v0
	v_mov_b32_e32 v70, v0
	v_mov_b32_e32 v71, v0
	v_mov_b32_e32 v76, v0
	v_mov_b32_e32 v77, v0
	v_mov_b32_e32 v78, v0
	v_mov_b32_e32 v79, v0
	v_mov_b32_e32 v80, v0
	v_mov_b32_e32 v81, v0
	v_mov_b32_e32 v82, v0
	v_mov_b32_e32 v83, v0
	v_mov_b32_e32 v92, v0
	v_mov_b32_e32 v93, v0
	v_mov_b32_e32 v94, v0
	v_mov_b32_e32 v95, v0
	v_mov_b32_e32 v96, v0
	v_mov_b32_e32 v97, v0
	v_mov_b32_e32 v98, v0
	v_mov_b32_e32 v99, v0
	v_mov_b32_e32 v108, v0
	v_mov_b32_e32 v109, v0
	v_mov_b32_e32 v110, v0
	v_mov_b32_e32 v111, v0
	v_mov_b32_e32 v112, v0
	v_mov_b32_e32 v113, v0
	v_mov_b32_e32 v114, v0
	v_mov_b32_e32 v115, v0
	v_mov_b32_e32 v72, v0
	v_mov_b32_e32 v73, v0
	v_mov_b32_e32 v74, v0
	v_mov_b32_e32 v75, v0
	v_mov_b32_e32 v84, v0
	v_mov_b32_e32 v85, v0
	v_mov_b32_e32 v86, v0
	v_mov_b32_e32 v87, v0
	v_mov_b32_e32 v88, v0
	v_mov_b32_e32 v89, v0
	v_mov_b32_e32 v90, v0
	v_mov_b32_e32 v91, v0
	v_mov_b32_e32 v100, v0
	v_mov_b32_e32 v101, v0
	v_mov_b32_e32 v102, v0
	v_mov_b32_e32 v103, v0
	v_mov_b32_e32 v104, v0
	v_mov_b32_e32 v105, v0
	v_mov_b32_e32 v106, v0
	v_mov_b32_e32 v107, v0
	v_mov_b32_e32 v116, v0
	v_mov_b32_e32 v117, v0
	v_mov_b32_e32 v118, v0
	v_mov_b32_e32 v119, v0
	v_mov_b32_e32 v120, v0
	v_mov_b32_e32 v121, v0
	v_mov_b32_e32 v122, v0
	v_mov_b32_e32 v123, v0
	v_mov_b32_e32 v124, v0
	v_mov_b32_e32 v125, v0
	v_mov_b32_e32 v126, v0
	v_mov_b32_e32 v127, v0
	v_lshl_add_u32 v240, s40, 8, v165
	v_lshl_or_b32 v242, s65, 8, v167
	v_ashrrev_i32_e32 v241, 31, v240
	v_ashrrev_i32_e32 v243, 31, v242
	v_lshlrev_b64 v[240:241], 10, v[240:241]
	v_lshl_add_u64 v[240:241], v[240:241], 0, v[242:243]
	v_lshlrev_b64 v[240:241], 1, v[240:241]
	v_lshl_add_u64 v[240:241], s[16:17], 0, v[240:241]
	.p2alignl 6, 3212836864

; template <class Epi, class Sched, bool ALIGN_EPI = false, bool SP2 = false>
; __device__ __forceinline__ void gemm_phase(PG8_LAS unsigned char* lds, const Gemm g, const Sched& S, const Epi& E, const int tid_in) {
;     ...
;         const bool has_next = S.next(ui + 1, nxt);
;         const char* nA = has_next ? (const char*)g.asel(nxt.pn) + (size_t)nxt.pm * tstep : cA; const char* nB = has_next ? (const char*)g.Bt + (size_t)nxt.pn * tstep : cB;
;     ...
; #pragma unroll
;         for (int a = 0; a < 2; ++a)
; #pragma unroll
;             for (int b = 0; b < 2; ++b)
; #pragma unroll
;                 for (int m = 0; m < 4; ++m)
; #pragma unroll
;                     for (int n = 0; n < 2; ++n) acc[a][b][m][n] = (f32x4){0.f, 0.f, 0.f, 0.f};
;         cur = nxt; cA = nA; cB = nB; ++ui;
.LBB0_1099:
	s_ashr_i32 s25, s24, 31
	s_lshl_b64 s[0:1], s[24:25], 17
	s_add_u32 s23, s52, s0
	s_addc_u32 s25, s53, s1
	s_and_b64 s[0:1], s[2:3], exec
	s_cselect_b32 s27, s25, s37
	s_cselect_b32 s26, s23, s36
	s_ashr_i32 s23, s22, 31
	s_lshl_b64 s[0:1], s[22:23], 17
	s_add_u32 s28, s56, s0
	s_addc_u32 s29, s57, s1
	s_and_b64 s[0:1], s[2:3], exec
	v_mov_b32_e32 v0, 0
	s_cselect_b32 s23, s29, s35
	s_cselect_b32 s25, s28, s34
	s_mov_b32 s40, 0
	s_mov_b64 s[0:1], -1
	s_mov_b64 s[38:39], 0
	v_mov_b32_e32 v1, v0
	v_mov_b32_e32 v2, v0
	v_mov_b32_e32 v3, v0
	v_mov_b32_e32 v4, v0
	v_mov_b32_e32 v5, v0
	v_mov_b32_e32 v6, v0
	v_mov_b32_e32 v7, v0
	v_mov_b32_e32 v8, v0
	v_mov_b32_e32 v9, v0
	v_mov_b32_e32 v10, v0
	v_mov_b32_e32 v11, v0
	v_mov_b32_e32 v16, v0
	v_mov_b32_e32 v17, v0
	v_mov_b32_e32 v18, v0
	v_mov_b32_e32 v19, v0
	v_mov_b32_e32 v24, v0
	v_mov_b32_e32 v25, v0
	v_mov_b32_e32 v26, v0
	v_mov_b32_e32 v27, v0
	v_mov_b32_e32 v32, v0
	v_mov_b32_e32 v33, v0
	v_mov_b32_e32 v34, v0
	v_mov_b32_e32 v35, v0
	v_mov_b32_e32 v40, v0
	v_mov_b32_e32 v41, v0
	v_mov_b32_e32 v42, v0
	v_mov_b32_e32 v43, v0
	v_mov_b32_e32 v48, v0
	v_mov_b32_e32 v49, v0
	v_mov_b32_e32 v50, v0
	v_mov_b32_e32 v51, v0
	v_mov_b32_e32 v12, v0
	v_mov_b32_e32 v13, v0
	v_mov_b32_e32 v14, v0
	v_mov_b32_e32 v15, v0
	v_mov_b32_e32 v20, v0
	v_mov_b32_e32 v21, v0
	v_mov_b32_e32 v22, v0
	v_mov_b32_e32 v23, v0
	v_mov_b32_e32 v28, v0
	v_mov_b32_e32 v29, v0
	v_mov_b32_e32 v30, v0
	v_mov_b32_e32 v31, v0
	v_mov_b32_e32 v36, v0
	v_mov_b32_e32 v37, v0
	v_mov_b32_e32 v38, v0
	v_mov_b32_e32 v39, v0
	v_mov_b32_e32 v44, v0
	v_mov_b32_e32 v45, v0
	v_mov_b32_e32 v46, v0
	v_mov_b32_e32 v47, v0
	v_mov_b32_e32 v52, v0
	v_mov_b32_e32 v53, v0
	v_mov_b32_e32 v54, v0
	v_mov_b32_e32 v55, v0
	v_mov_b32_e32 v56, v0
	v_mov_b32_e32 v57, v0
	v_mov_b32_e32 v58, v0
	v_mov_b32_e32 v59, v0
	v_mov_b32_e32 v60, v0
	v_mov_b32_e32 v61, v0
	v_mov_b32_e32 v62, v0
	v_mov_b32_e32 v63, v0
	v_mov_b32_e32 v64, v0
	v_mov_b32_e32 v65, v0
	v_mov_b32_e32 v66, v0
	v_mov_b32_e32 v67, v0
	v_mov_b32_e32 v68, v0
	v_mov_b32_e32 v69, v0
	v_mov_b32_e32 v70, v0
	v_mov_b32_e32 v71, v0
	v_mov_b32_e32 v72, v0
	v_mov_b32_e32 v73, v0
	v_mov_b32_e32 v74, v0
	v_mov_b32_e32 v75, v0
	v_mov_b32_e32 v80, v0
	v_mov_b32_e32 v81, v0
	v_mov_b32_e32 v82, v0
	v_mov_b32_e32 v83, v0
	v_mov_b32_e32 v88, v0
	v_mov_b32_e32 v89, v0
	v_mov_b32_e32 v90, v0
	v_mov_b32_e32 v91, v0
	v_mov_b32_e32 v96, v0
	v_mov_b32_e32 v97, v0
	v_mov_b32_e32 v98, v0
	v_mov_b32_e32 v99, v0
	v_mov_b32_e32 v104, v0
	v_mov_b32_e32 v105, v0
	v_mov_b32_e32 v106, v0
	v_mov_b32_e32 v107, v0
	v_mov_b32_e32 v112, v0
	v_mov_b32_e32 v113, v0
	v_mov_b32_e32 v114, v0
	v_mov_b32_e32 v115, v0
	v_mov_b32_e32 v76, v0
	v_mov_b32_e32 v77, v0
	v_mov_b32_e32 v78, v0
	v_mov_b32_e32 v79, v0
	v_mov_b32_e32 v84, v0
	v_mov_b32_e32 v85, v0
	v_mov_b32_e32 v86, v0
	v_mov_b32_e32 v87, v0
	v_mov_b32_e32 v92, v0
	v_mov_b32_e32 v93, v0
	v_mov_b32_e32 v94, v0
	v_mov_b32_e32 v95, v0
	v_mov_b32_e32 v100, v0
	v_mov_b32_e32 v101, v0
	v_mov_b32_e32 v102, v0
	v_mov_b32_e32 v103, v0
	v_mov_b32_e32 v108, v0
	v_mov_b32_e32 v109, v0
	v_mov_b32_e32 v110, v0
	v_mov_b32_e32 v111, v0
	v_mov_b32_e32 v116, v0
	v_mov_b32_e32 v117, v0
	v_mov_b32_e32 v118, v0
	v_mov_b32_e32 v119, v0
	v_mov_b32_e32 v120, v0
	v_mov_b32_e32 v121, v0
	v_mov_b32_e32 v122, v0
	v_mov_b32_e32 v123, v0
	v_mov_b32_e32 v124, v0
	v_mov_b32_e32 v125, v0
	v_mov_b32_e32 v126, v0
	v_mov_b32_e32 v127, v0
	.p2alignl 6, 3212836864
